# attention main loop: one workgroup barrier per two key tiles (mid-iteration wait ladder+barrier removed, its LDS-DMA issue moved behind the iteration-end barrier with vmcnt(0)), on top of combined
# speedup vs baseline: 1.0078x; 1.0015x over previous
; #define ATT_BAR() asm volatile("s_waitcnt lgkmcnt(0)\n\ts_barrier" ::: "memory")
; #define WAIT_TILES2() do { if (wid < 4) { ATT_WAITV(6); } else { ATT_WAITV(4); } } while (0)
; __device__ __forceinline__ void attn_unit(const bf16_t* __restrict__ Qb, const unsigned char* __restrict__ Kn, const unsigned char* __restrict__ Vp, const unsigned char* __restrict__ Kp, ...
;     ...
;   WAIT_TILES2(); ATT_BAR();
;   ISSUE(5, 5 * KVBLK);
.LBB0_645:
	s_mov_b64 s[58:59], 0xa000
	s_waitcnt vmcnt(0)
	s_waitcnt lgkmcnt(0)
	s_barrier
	v_lshl_add_u64 v[38:39], v[52:53], 0, s[58:59]
	s_add_i32 m0, s8, 0xa000
	s_mov_b64 s[58:59], 0x140000
	global_load_lds_dwordx4 v[38:39], off
	v_lshl_add_u64 v[0:1], v[0:1], 0, s[58:59]
	s_add_i32 m0, s8, 0x16000
	s_andn2_b64 vcc, exec, s[80:81]
	global_load_lds_dwordx4 v[0:1], off
	s_cbranch_vccnz .LBB0_647
	s_cbranch_execz .LBB0_648
	s_branch .LBB0_649

.LBB0_650:
	v_sub_co_u32_e64 v0, s[38:39], s62, 1
	s_and_b64 s[38:39], s[38:39], exec
	v_readfirstlane_b32 s9, v0
	s_cselect_b32 s60, 5, s9
	s_mov_b32 s32, s60
	s_add_i32 s9, s62, 1
	s_cmp_lg_u32 s62, 5
	s_cselect_b32 s9, s9, 0
	s_lshl_b32 s61, s60, 13
	v_add_u32_e32 v2, s61, v239
	v_add_u32_e32 v250, s61, v240
	v_lshl_add_u32 v0, s62, 12, v238
	v_add_u32_e32 v1, v0, v231
	v_add_u32_e32 v0, v0, v232
	ds_read_b128 v[242:245], v1
	ds_read_b128 v[202:205], v1 offset:2048
	ds_read_b128 v[246:249], v0
	ds_read_b128 v[206:209], v0 offset:2048
	s_waitcnt lgkmcnt(4)
	v_mfma_f32_32x32x64_f8f6f4 v[132:147], v[116:123], v[148:155], v[68:83]
	v_exp_f32_e32 v100, v100
	v_exp_f32_e32 v101, v101
	v_exp_f32_e32 v102, v102
	v_exp_f32_e32 v103, v103
	v_exp_f32_e32 v104, v104
	v_exp_f32_e32 v105, v105
	v_exp_f32_e32 v106, v106
	v_exp_f32_e32 v107, v107
	v_pk_add_f32 v[0:1], v[100:101], v[102:103]
	v_pk_add_f32 v[252:253], v[104:105], v[106:107]
	v_mfma_f32_32x32x64_f8f6f4 v[116:131], v[188:195], v[148:155], v[68:83]
	v_exp_f32_e32 v108, v108
	v_exp_f32_e32 v109, v109
	v_exp_f32_e32 v110, v110
	v_exp_f32_e32 v111, v111
	v_exp_f32_e32 v112, v112
	v_exp_f32_e32 v113, v113
	v_exp_f32_e32 v114, v114
	v_exp_f32_e32 v115, v115
	v_pk_add_f32 v[0:1], v[108:109], v[0:1]
	v_pk_add_f32 v[252:253], v[252:253], v[110:111]
	v_pk_add_f32 v[0:1], v[112:113], v[0:1]
	v_pk_add_f32 v[252:253], v[252:253], v[114:115]
	v_mfma_f32_32x32x64_f8f6f4 v[132:147], v[180:187], v[156:163], v[132:147]
	v_exp_f32_e32 v84, v84
	v_exp_f32_e32 v85, v85
	v_exp_f32_e32 v86, v86
	v_exp_f32_e32 v87, v87
	v_exp_f32_e32 v88, v88
	v_exp_f32_e32 v89, v89
	v_exp_f32_e32 v90, v90
	v_exp_f32_e32 v91, v91
	v_pk_add_f32 v[0:1], v[84:85], v[0:1]
	v_pk_add_f32 v[252:253], v[252:253], v[86:87]
	v_pk_add_f32 v[0:1], v[88:89], v[0:1]
	v_pk_add_f32 v[252:253], v[252:253], v[90:91]
	v_mfma_f32_32x32x64_f8f6f4 v[116:131], v[172:179], v[156:163], v[116:131]
	ds_read_b64 v[182:183], v250
	ds_read_b64 v[176:177], v250 offset:2048
	ds_read_b128 v[178:181], v2
	ds_read_b128 v[172:175], v2 offset:2048
	v_exp_f32_e32 v92, v92
	v_exp_f32_e32 v93, v93
	v_exp_f32_e32 v94, v94
	v_exp_f32_e32 v95, v95
	v_exp_f32_e32 v96, v96
	v_exp_f32_e32 v97, v97
	v_exp_f32_e32 v98, v98
	v_exp_f32_e32 v99, v99
	v_pk_add_f32 v[0:1], v[92:93], v[0:1]
	v_pk_add_f32 v[252:253], v[252:253], v[94:95]
	v_pk_add_f32 v[0:1], v[96:97], v[0:1]
	v_pk_add_f32 v[252:253], v[252:253], v[98:99]
	v_cvt_scalef32_2xpk16_bf6_f32 v[196:201], v[100:115], v[84:99], 1.0
	v_pk_add_f32 v[0:1], v[0:1], v[252:253]
	s_waitcnt lgkmcnt(4)
	v_mfma_f32_32x32x64_f8f6f4 v[132:147], v[242:249], v[164:171], v[132:147]
	s_nop 0
	v_pk_add_f32 v[0:1], v[0:1], v[0:1] op_sel:[0,1] op_sel_hi:[1,0]
	s_nop 0
	v_mov_b32_e32 v1, v0
	s_nop 1
	v_permlane32_swap_b32_e32 v0, v1
	v_mfma_f32_32x32x64_f8f6f4 v[116:131], v[202:209], v[164:171], v[116:131]
	s_waitcnt lgkmcnt(0)
	v_mfma_f32_32x32x64_f8f6f4 v[52:67], v[196:201], v[178:183], v[52:67] cbsz:3 blgp:2
	ds_read_b64 v[102:103], v250 offset:4096
	ds_read_b64 v[96:97], v250 offset:6144
	ds_read_b128 v[98:101], v2 offset:4096
	ds_read_b128 v[92:95], v2 offset:6144
	v_max3_f32 v84, v132, v133, v134
	v_max3_f32 v2, v135, v136, v137
	v_max3_f32 v84, v84, v138, v139
	s_nop 0
	v_max3_f32 v2, v2, v140, v141
	v_max3_f32 v84, v84, v142, v143
	s_nop 0
	v_max3_f32 v2, v2, v144, v145
	v_max3_f32 v84, v84, v146, v147
	v_mfma_f32_32x32x64_f8f6f4 v[36:51], v[196:201], v[172:177], v[36:51] cbsz:3 blgp:2
	v_lshl_add_u32 v105, s9, 13, v233
	v_max3_f32 v84, v84, v116, v117
	v_add_u32_e32 v88, v105, v234
	v_add_u32_e32 v106, v105, v235
	v_max3_f32 v104, v84, v120, v121
	ds_read_b128 v[84:87], v88 offset:49152
	ds_read_b128 v[188:191], v88 offset:53248
	ds_read_b128 v[88:91], v106 offset:49152
	ds_read_b128 v[192:195], v106 offset:53248
	v_add_u32_e32 v106, v105, v236
	v_add_u32_e32 v105, v105, v237
	ds_read_b128 v[180:183], v106 offset:49152
	ds_read_b128 v[172:175], v106 offset:53248
	ds_read_b128 v[184:187], v105 offset:49152
	ds_read_b128 v[176:179], v105 offset:53248
	v_max3_f32 v2, v2, v118, v119
	v_max3_f32 v104, v104, v124, v125
	s_nop 0
	v_max3_f32 v2, v2, v122, v123
	v_max3_f32 v104, v104, v128, v129
	s_nop 0
	v_max3_f32 v2, v2, v126, v127
	s_nop 0
	v_max3_f32 v2, v2, v130, v131
	s_waitcnt lgkmcnt(8)
	v_mfma_f32_32x32x64_f8f6f4 v[20:35], v[196:201], v[98:103], v[20:35] cbsz:3 blgp:2
	v_max_f32_e32 v2, v2, v2
	v_max_f32_e32 v98, v104, v104
	v_max_f32_e32 v2, v98, v2
	v_mov_b32_e32 v98, v2
	s_nop 1
	v_permlane32_swap_b32_e32 v2, v98
	v_max_f32_e32 v98, v98, v98
	v_max_f32_e32 v2, v2, v2
	v_max_f32_e32 v2, v2, v98
	v_cmp_ge_f32_e32 vcc, s0, v2
	s_cmp_eq_u64 vcc, exec
	s_cbranch_scc0 .LBB0_683
	v_mov_b32_e32 v242, 1.0

.LBB0_656:
	s_waitcnt lgkmcnt(0)
	v_cndmask_b32_e64 v2, 0, 1, s[28:29]
	v_cmp_ne_u32_e64 s[38:39], 1, v2

.LBB0_671:
	s_waitcnt vmcnt(0)
	s_waitcnt lgkmcnt(0)
	s_barrier
	s_add_i32 s58, s2, -1
	s_cmp_ge_u32 s58, s92
	s_cbranch_scc1 .Lattn_xdone
	s_lshl_b32 s58, s32, 13
	s_add_i32 s58, s8, s58
	v_lshl_add_u64 v[124:125], v[218:219], 0, s[96:97]
	s_mov_b32 m0, s58
	s_and_b64 vcc, exec, s[38:39]
	global_load_lds_dwordx4 v[124:125], off
	v_lshl_add_u64 v[124:125], v[216:217], 0, s[96:97]
	s_add_i32 m0, s58, 0xc000
	s_nop 0
	global_load_lds_dwordx4 v[124:125], off
	s_cbranch_vccnz .Lattn_xdone
	s_mov_b32 s100, 0xfffff000
	s_mov_b32 s101, -1
	s_lshl_b32 s59, s32, 12
	v_lshl_add_u64 v[124:125], v[210:211], 0, s[100:101]
	s_add_i32 m0, s57, s59
	s_nop 0
	global_load_lds_dwordx4 v[124:125], off
.Lattn_xdone:
	s_cmp_ge_u32 s2, s92
	s_cbranch_scc1 .LBB0_681
	s_add_i32 s58, s8, s64
	v_lshl_add_u64 v[124:125], v[214:215], 0, s[96:97]
	s_mov_b32 m0, s58
	s_and_b64 vcc, exec, s[38:39]
	global_load_lds_dwordx4 v[124:125], off
	v_lshl_add_u64 v[124:125], v[212:213], 0, s[96:97]
	s_add_i32 m0, s58, 0xc000
	s_nop 0
	global_load_lds_dwordx4 v[124:125], off
	s_cbranch_vccnz .LBB0_681
	s_lshl_b32 s38, s63, 12
	s_add_i32 m0, s57, s38
	s_nop 0
	global_load_lds_dwordx4 v[210:211], off

; __global__ void __launch_bounds__(NWAVES * 64, 2) fwd(Args args) {
	.amdhsa_kernel _Z3fwd4Args
		.amdhsa_group_segment_fixed_size 0
		.amdhsa_private_segment_fixed_size 0
		.amdhsa_kernarg_size 464
		.amdhsa_user_sgpr_count 2
		.amdhsa_user_sgpr_dispatch_ptr 0
		.amdhsa_user_sgpr_queue_ptr 0
		.amdhsa_user_sgpr_kernarg_segment_ptr 1
		.amdhsa_user_sgpr_dispatch_id 0
		.amdhsa_user_sgpr_kernarg_preload_length 0
		.amdhsa_user_sgpr_kernarg_preload_offset 0
		.amdhsa_user_sgpr_private_segment_size 0
		.amdhsa_uses_dynamic_stack 0
		.amdhsa_enable_private_segment 0
		.amdhsa_system_sgpr_workgroup_id_x 1
		.amdhsa_system_sgpr_workgroup_id_y 0
		.amdhsa_system_sgpr_workgroup_id_z 0
		.amdhsa_system_sgpr_workgroup_info 0
		.amdhsa_system_vgpr_workitem_id 0
		.amdhsa_next_free_vgpr 256
		.amdhsa_next_free_sgpr 102
		.amdhsa_accum_offset 256
		.amdhsa_reserve_vcc 1
		.amdhsa_float_round_mode_32 0
		.amdhsa_float_round_mode_16_64 0
		.amdhsa_float_denorm_mode_32 3
		.amdhsa_float_denorm_mode_16_64 3
		.amdhsa_dx10_clamp 1
		.amdhsa_ieee_mode 1
		.amdhsa_fp16_overflow 0
		.amdhsa_tg_split 0
		.amdhsa_exception_fp_ieee_invalid_op 0
		.amdhsa_exception_fp_denorm_src 0
		.amdhsa_exception_fp_ieee_div_zero 0
		.amdhsa_exception_fp_ieee_overflow 0
		.amdhsa_exception_fp_ieee_underflow 0
		.amdhsa_exception_fp_ieee_inexact 0
		.amdhsa_exception_int_div_zero 0
	.end_amdhsa_kernel

; __global__ void __launch_bounds__(NWAVES * 64, 2) fwd(Args args) {
amdhsa.kernels:
  - .agpr_count:     0
    .args:
      - .offset:         0
        .size:           208
        .value_kind:     by_value
      - .offset:         208
        .size:           4
        .value_kind:     hidden_block_count_x
      - .offset:         212
        .size:           4
        .value_kind:     hidden_block_count_y
      - .offset:         216
        .size:           4
        .value_kind:     hidden_block_count_z
      - .offset:         220
        .size:           2
        .value_kind:     hidden_group_size_x
      - .offset:         222
        .size:           2
        .value_kind:     hidden_group_size_y
      - .offset:         224
        .size:           2
        .value_kind:     hidden_group_size_z
      - .offset:         226
        .size:           2
        .value_kind:     hidden_remainder_x
      - .offset:         228
        .size:           2
        .value_kind:     hidden_remainder_y
      - .offset:         230
        .size:           2
        .value_kind:     hidden_remainder_z
      - .offset:         248
        .size:           8
        .value_kind:     hidden_global_offset_x
      - .offset:         256
        .size:           8
        .value_kind:     hidden_global_offset_y
      - .offset:         264
        .size:           8
        .value_kind:     hidden_global_offset_z
      - .offset:         272
        .size:           2
        .value_kind:     hidden_grid_dims
      - .offset:         328
        .size:           4
        .value_kind:     hidden_dynamic_lds_size
    .group_segment_fixed_size: 0
    .kernarg_segment_align: 8
    .kernarg_segment_size: 464
    .language:       OpenCL C
    .language_version:
      - 2
      - 0
    .max_flat_workgroup_size: 512
    .name:           _Z3fwd4Args
    .private_segment_fixed_size: 0
    .sgpr_count:     108
    .sgpr_spill_count: 78
    .symbol:         _Z3fwd4Args.kd
    .uniform_work_group_size: 1
    .uses_dynamic_stack: false
    .vgpr_count:     256
    .vgpr_spill_count: 0
    .wavefront_size: 64
